# v23 + attention tile bodies (GQA, diff): K/V fragment LDS addresses carried across tiles and toggled at the body end instead of being recomputed at each tile start
# speedup vs baseline: 1.0090x; 1.0044x over previous
; template <int DQ, bool NA, int NQG>
; DI void attn_wg(const half_t* Qp, const half_t* Kp, const half_t* Vp, int q0, bool active, int seg0_start, int seg0_tiles,
;                 int seg1_start, int seg1_tiles, const float* rpb_h, int rq, char* smem, int tid, f16v (&O)[2][NQG]) {
;     ...
;   float mrun[NQG], lrun[NQG];
; #pragma unroll
;   for (int qg = 0; qg < NQG; ++qg) { mrun[qg] = -1e30f; lrun[qg] = 0.f; }
; #pragma unroll
;   for (int a = 0; a < 2; ++a)
; #pragma unroll
;     for (int c = 0; c < NQG; ++c)
; #pragma unroll
;       for (int i = 0; i < 16; ++i) O[a][c][i] = 0.f;
;   const int ntiles = seg0_tiles + seg1_tiles;
;   const int kc0 = tid, kc1 = tid + 512;
;   const half_t* kg0 = Kp + kc0 * 8;
;   const half_t* kg1 = Kp + kc1 * 8;
;   const half_t* vg = Vp + (size_t)(tid >> 3) * TOK + (tid & 7) * 8;
;   const int ks0 = (kc0 / CPK) * KSTR + (kc0 % CPK) * 8, ks1 = (kc1 / CPK) * KSTR + (kc1 % CPK) * 8, vs0 = (tid >> 3) * VSTR + (tid & 7) * 8;
;   uint4 kreg0 = {0, 0, 0, 0}, kreg1 = {0, 0, 0, 0}, vreg;
;   const int r0w = min(max(rq - 4, 0), 24);
;   {
;     const int k0 = (0 < seg0_tiles) ? seg0_start : seg1_start;
;     if (kc0 < KCH) kreg0 = *(const uint4*)(kg0 + (size_t)k0 * DQ);
;     if (DQ == 96 && kc1 < KCH) kreg1 = *(const uint4*)(kg1 + (size_t)k0 * DQ);
;     vreg = *(const uint4*)(vg + k0);
;     if (kc0 < KCH) *(uint4*)((half_t*)smem + ks0) = kreg0;
;     if (DQ == 96 && kc1 < KCH) *(uint4*)((half_t*)smem + ks1) = kreg1;
;     *(uint4*)((half_t*)(smem + ATT_VOFF) + vs0) = vreg;
;   }
;   __syncthreads();
;     ...
;     const half_t* ksm = (const half_t*)(smem + (it & 1) * ATT_STAGE) + r * KSTR + h * 8;
;     const half_t* vsm = (const half_t*)(smem + (it & 1) * ATT_STAGE + ATT_VOFF) + r * VSTR + h * 4;
.LBB0_1912:
	s_or_b64 exec, exec, s[6:7]
	v_mov_b32_e32 v14, v0
	v_mov_b32_e32 v15, v0
	v_mov_b32_e32 v1, v0
	v_mov_b32_e32 v2, v0
	v_mov_b32_e32 v3, v0
	v_mov_b32_e32 v4, v0
	v_mov_b32_e32 v5, v0
	v_mov_b32_e32 v6, v0
	v_mov_b32_e32 v7, v0
	v_mov_b32_e32 v8, v0
	v_mov_b32_e32 v9, v0
	v_mov_b32_e32 v10, v0
	v_mov_b32_e32 v11, v0
	v_mov_b32_e32 v12, v0
	v_mov_b32_e32 v13, v0
	v_mov_b64_e32 v[64:65], v[14:15]
	v_mov_b64_e32 v[32:33], v[14:15]
	v_mov_b64_e32 v[48:49], v[14:15]
	v_mov_b64_e32 v[62:63], v[12:13]
	v_mov_b64_e32 v[60:61], v[10:11]
	v_mov_b64_e32 v[58:59], v[8:9]
	v_mov_b64_e32 v[56:57], v[6:7]
	v_mov_b64_e32 v[54:55], v[4:5]
	v_mov_b64_e32 v[52:53], v[2:3]
	v_mov_b64_e32 v[50:51], v[0:1]
	v_mov_b64_e32 v[30:31], v[12:13]
	v_mov_b64_e32 v[28:29], v[10:11]
	v_mov_b64_e32 v[26:27], v[8:9]
	v_mov_b64_e32 v[24:25], v[6:7]
	v_mov_b64_e32 v[22:23], v[4:5]
	v_mov_b64_e32 v[20:21], v[2:3]
	v_mov_b64_e32 v[18:19], v[0:1]
	v_mov_b64_e32 v[46:47], v[12:13]
	v_mov_b64_e32 v[44:45], v[10:11]
	v_mov_b64_e32 v[42:43], v[8:9]
	v_mov_b64_e32 v[40:41], v[6:7]
	v_mov_b64_e32 v[38:39], v[4:5]
	v_mov_b64_e32 v[36:37], v[2:3]
	v_mov_b64_e32 v[34:35], v[0:1]
	v_mov_b64_e32 v[16:17], v[14:15]
	s_mov_b32 s22, 0
	v_mov_b32_e32 v194, 0xf149f2ca
	v_mov_b32_e32 v183, 0
	v_mov_b64_e32 v[14:15], v[12:13]
	v_mov_b64_e32 v[12:13], v[10:11]
	v_mov_b64_e32 v[10:11], v[8:9]
	v_mov_b64_e32 v[8:9], v[6:7]
	v_mov_b64_e32 v[6:7], v[4:5]
	v_mov_b64_e32 v[4:5], v[2:3]
	v_mov_b64_e32 v[2:3], v[0:1]
	v_mov_b32_e32 v1, 0
	v_mov_b32_e32 v196, 0xf149f2ca
	s_waitcnt vmcnt(0)
	ds_write_b128 v195, v[134:137] offset:13312
	s_waitcnt lgkmcnt(0)
	s_barrier
	v_add3_u32 v187, 0, v237, v156
	v_add3_u32 v189, 0, v237, v155
	v_add_u32_e32 v197, 0x4600, v189
	v_add_u32_e32 v189, 0x3400, v189

; template <int DQ, bool NA, int NQG>
; DI void attn_wg(const half_t* Qp, const half_t* Kp, const half_t* Vp, int q0, bool active, int seg0_start, int seg0_tiles,
;                 int seg1_start, int seg1_tiles, const float* rpb_h, int rq, char* smem, int tid, f16v (&O)[2][NQG]) {
;     ...
;     if (need) {
; #pragma unroll 1
;       for (int st = 0; st < 2; ++st) {
;         f16v S[NQG];
; #pragma unroll
;         for (int qg = 0; qg < NQG; ++qg)
; #pragma unroll
;           for (int i = 0; i < 16; ++i) S[qg][i] = 0.f;
; #pragma unroll
;         for (int ks = 0; ks < NKS; ++ks) {
;           const h8 kf = *(const h8*)(ksm + (st * 32) * KSTR + ks * 16);
; #pragma unroll
;           for (int qg = 0; qg < NQG; ++qg) S[qg] = __builtin_amdgcn_mfma_f32_32x32x16_f16(kf, qf[qg][ks], S[qg], 0, 0, 0);
;     ...
;           const float mn = mrun[qg];
;           f2 rs2 = {0.f, 0.f};
;           const f2 mn2 = {mn, mn};
; #pragma unroll
;           for (int i = 0; i < 16; i += 2) {
;             const f2 s2 = {S[qg][i], S[qg][i + 1]};
;             const f2 d2 = s2 - mn2;
;             f2 p2;
;             p2.x = __builtin_amdgcn_exp2f(d2.x);
;             p2.y = __builtin_amdgcn_exp2f(d2.y);
;             if (NA) { p2.x = (s2.x <= -1e29f) ? 0.f : p2.x; p2.y = (s2.y <= -1e29f) ? 0.f : p2.y; }
;             rs2 += p2;
;             P[i >> 3][i & 7] = (half_t)p2.x;
;             P[i >> 3][(i & 7) + 1] = (half_t)p2.y;
;           }
.LBB0_1917:
	v_cndmask_b32_e64 v66, 0, 1, s[14:15]
	v_cmp_ne_u32_e64 s[6:7], 1, v66
	s_andn2_b64 vcc, exec, s[14:15]
	s_cbranch_vccnz .LBB0_1924
	s_bitcmp1_b32 s22, 0
	s_cselect_b32 s22, 0x5800, 0
	ds_read_b128 v[198:201], v187 offset:0
	ds_read_b128 v[202:205], v187 offset:32
	ds_read_b128 v[206:209], v187 offset:64
	ds_read_b128 v[210:213], v187 offset:96
	ds_read2_b64 v[138:141], v189 offset0:0 offset1:2
	ds_read2_b64 v[142:145], v189 offset0:4 offset1:6
	ds_read2_b64 v[146:149], v197 offset0:0 offset1:2
	ds_read2_b64 v[150:153], v197 offset0:4 offset1:6
	s_waitcnt lgkmcnt(7)
	v_mfma_f32_32x32x16_f16 v[82:97], v[198:201], v[98:101], 0
	s_waitcnt lgkmcnt(6)
	v_mfma_f32_32x32x16_f16 v[82:97], v[202:205], v[102:105], v[82:97]
	s_waitcnt lgkmcnt(5)
	v_mfma_f32_32x32x16_f16 v[82:97], v[206:209], v[106:109], v[82:97]
	s_waitcnt lgkmcnt(4)
	v_mfma_f32_32x32x16_f16 v[82:97], v[210:213], v[110:113], v[82:97]
	s_nop 11
	v_pk_add_f32 v[82:83], v[82:83], v[194:195] op_sel_hi:[1,0] neg_lo:[0,1] neg_hi:[0,1]
	v_pk_add_f32 v[84:85], v[84:85], v[194:195] op_sel_hi:[1,0] neg_lo:[0,1] neg_hi:[0,1]
	v_exp_f32_e32 v82, v82
	v_exp_f32_e32 v83, v83
	v_pk_add_f32 v[86:87], v[86:87], v[194:195] op_sel_hi:[1,0] neg_lo:[0,1] neg_hi:[0,1]
	v_mfma_f32_32x32x16_f16 v[66:81], v[198:201], v[114:117], 0
	v_exp_f32_e32 v84, v84
	v_exp_f32_e32 v85, v85
	v_pk_add_f32 v[88:89], v[88:89], v[194:195] op_sel_hi:[1,0] neg_lo:[0,1] neg_hi:[0,1]
	v_exp_f32_e32 v86, v86
	v_exp_f32_e32 v87, v87
	v_pk_add_f32 v[90:91], v[90:91], v[194:195] op_sel_hi:[1,0] neg_lo:[0,1] neg_hi:[0,1]
	v_exp_f32_e32 v88, v88
	v_mfma_f32_32x32x16_f16 v[66:81], v[202:205], v[118:121], v[66:81]
	v_exp_f32_e32 v89, v89
	v_pk_add_f32 v[92:93], v[92:93], v[194:195] op_sel_hi:[1,0] neg_lo:[0,1] neg_hi:[0,1]
	v_exp_f32_e32 v90, v90
	v_exp_f32_e32 v91, v91
	v_pk_add_f32 v[94:95], v[94:95], v[194:195] op_sel_hi:[1,0] neg_lo:[0,1] neg_hi:[0,1]
	v_exp_f32_e32 v92, v92
	v_exp_f32_e32 v93, v93
	v_mfma_f32_32x32x16_f16 v[66:81], v[206:209], v[122:125], v[66:81]
	v_pk_add_f32 v[96:97], v[96:97], v[194:195] op_sel_hi:[1,0] neg_lo:[0,1] neg_hi:[0,1]
	v_exp_f32_e32 v94, v94
	v_exp_f32_e32 v95, v95
	v_exp_f32_e32 v96, v96
	v_exp_f32_e32 v97, v97
	v_cvt_pk_f16_f32 v214, v82, v83
	v_cvt_pk_f16_f32 v215, v84, v85
	v_mfma_f32_32x32x16_f16 v[66:81], v[210:213], v[126:129], v[66:81]
	v_cvt_pk_f16_f32 v216, v86, v87
	v_cvt_pk_f16_f32 v217, v88, v89
	v_cvt_pk_f16_f32 v218, v90, v91
	v_cvt_pk_f16_f32 v219, v92, v93
	v_cvt_pk_f16_f32 v220, v94, v95
	v_cvt_pk_f16_f32 v221, v96, v97
	v_pk_add_f32 v[222:223], v[82:83], v[84:85]
	v_pk_add_f32 v[224:225], v[86:87], v[88:89]
	v_pk_add_f32 v[226:227], v[90:91], v[92:93]
	v_pk_add_f32 v[228:229], v[94:95], v[96:97]
	v_pk_add_f32 v[222:223], v[222:223], v[224:225]
	v_pk_add_f32 v[226:227], v[226:227], v[228:229]
	v_pk_add_f32 v[222:223], v[222:223], v[226:227]
	v_add_f32_e32 v222, v222, v223
	v_cmp_lt_f32_e32 vcc, 0x43800000, v222
	s_cbranch_vccnz .Leager_gqa_0

; template <int DQ, bool NA, int NQG>
; DI void attn_wg(const half_t* Qp, const half_t* Kp, const half_t* Vp, int q0, bool active, int seg0_start, int seg0_tiles,
;                 int seg1_start, int seg1_tiles, const float* rpb_h, int rq, char* smem, int tid, f16v (&O)[2][NQG]) {
;     ...
;           lrun[qg] += rs2.x + rs2.y;
; #pragma unroll
;           for (int dvt = 0; dvt < 2; ++dvt) {
; #pragma unroll
;             for (int sx = 0; sx < 2; ++sx) {
;               const h8 va = __builtin_shufflevector(vf[dvt][sx][0], vf[dvt][sx][1], 0, 1, 2, 3, 4, 5, 6, 7);
;               O[dvt][qg] = __builtin_amdgcn_mfma_f32_32x32x16_f16(va, P[sx], O[dvt][qg], 0, 0, 0);
;             }
.Lcont_gqa_3:
	v_add_f32_e32 v1, v1, v222
	v_mfma_f32_32x32x16_f16 v[34:49], v[138:141], v[214:217], v[34:49]
	v_mfma_f32_32x32x16_f16 v[50:65], v[146:149], v[214:217], v[50:65]
	v_mfma_f32_32x32x16_f16 v[34:49], v[142:145], v[218:221], v[34:49]
	v_mfma_f32_32x32x16_f16 v[50:65], v[150:153], v[218:221], v[50:65]
	s_lshl_b32 s40, s22, 1
	s_sub_u32 s40, 0x5800, s40
	v_add_u32_e32 v187, s40, v187
	v_add_u32_e32 v189, s40, v189
	v_add_u32_e32 v197, s40, v197
	s_branch .Lend_gqa

; template <int DQ, bool NA, int NQG>
; DI void attn_wg(const half_t* Qp, const half_t* Kp, const half_t* Vp, int q0, bool active, int seg0_start, int seg0_tiles,
;                 int seg1_start, int seg1_tiles, const float* rpb_h, int rq, char* smem, int tid, f16v (&O)[2][NQG]) {
;     ...
;   float mrun[NQG], lrun[NQG];
; #pragma unroll
;   for (int qg = 0; qg < NQG; ++qg) { mrun[qg] = -1e30f; lrun[qg] = 0.f; }
; #pragma unroll
;   for (int a = 0; a < 2; ++a)
; #pragma unroll
;     for (int c = 0; c < NQG; ++c)
; #pragma unroll
;       for (int i = 0; i < 16; ++i) O[a][c][i] = 0.f;
;   const int ntiles = seg0_tiles + seg1_tiles;
;   const int kc0 = tid, kc1 = tid + 512;
;   const half_t* kg0 = Kp + kc0 * 8;
;   const half_t* kg1 = Kp + kc1 * 8;
;   const half_t* vg = Vp + (size_t)(tid >> 3) * TOK + (tid & 7) * 8;
;   const int ks0 = (kc0 / CPK) * KSTR + (kc0 % CPK) * 8, ks1 = (kc1 / CPK) * KSTR + (kc1 % CPK) * 8, vs0 = (tid >> 3) * VSTR + (tid & 7) * 8;
;   uint4 kreg0 = {0, 0, 0, 0}, kreg1 = {0, 0, 0, 0}, vreg;
;   const int r0w = min(max(rq - 4, 0), 24);
;   {
;     const int k0 = (0 < seg0_tiles) ? seg0_start : seg1_start;
;     if (kc0 < KCH) kreg0 = *(const uint4*)(kg0 + (size_t)k0 * DQ);
;     if (DQ == 96 && kc1 < KCH) kreg1 = *(const uint4*)(kg1 + (size_t)k0 * DQ);
;     vreg = *(const uint4*)(vg + k0);
;     if (kc0 < KCH) *(uint4*)((half_t*)smem + ks0) = kreg0;
;     if (DQ == 96 && kc1 < KCH) *(uint4*)((half_t*)smem + ks1) = kreg1;
;     *(uint4*)((half_t*)(smem + ATT_VOFF) + vs0) = vreg;
;   }
;   __syncthreads();
;     ...
;     const half_t* ksm = (const half_t*)(smem + (it & 1) * ATT_STAGE) + r * KSTR + h * 8;
;     const half_t* vsm = (const half_t*)(smem + (it & 1) * ATT_STAGE + ATT_VOFF) + r * VSTR + h * 4;
.LBB0_2034:
	s_or_b64 exec, exec, s[6:7]
	v_mov_b32_e32 v14, v0
	v_mov_b32_e32 v15, v0
	v_mov_b32_e32 v1, v0
	v_mov_b32_e32 v2, v0
	v_mov_b32_e32 v3, v0
	v_mov_b32_e32 v4, v0
	v_mov_b32_e32 v5, v0
	v_mov_b32_e32 v6, v0
	v_mov_b32_e32 v7, v0
	v_mov_b32_e32 v8, v0
	v_mov_b32_e32 v9, v0
	v_mov_b32_e32 v10, v0
	v_mov_b32_e32 v11, v0
	v_mov_b32_e32 v12, v0
	v_mov_b32_e32 v13, v0
	v_mov_b64_e32 v[30:31], v[14:15]
	v_mov_b64_e32 v[46:47], v[14:15]
	v_mov_b64_e32 v[62:63], v[14:15]
	v_mov_b64_e32 v[78:79], v[14:15]
	s_mov_b32 s18, 0
	s_waitcnt vmcnt(5)
	v_mov_b32_e32 v148, 0xf149f2ca
	v_mov_b32_e32 v149, 0
	v_mov_b64_e32 v[28:29], v[12:13]
	v_mov_b64_e32 v[26:27], v[10:11]
	v_mov_b64_e32 v[24:25], v[8:9]
	v_mov_b64_e32 v[22:23], v[6:7]
	v_mov_b64_e32 v[20:21], v[4:5]
	v_mov_b64_e32 v[18:19], v[2:3]
	v_mov_b64_e32 v[16:17], v[0:1]
	v_mov_b64_e32 v[44:45], v[12:13]
	v_mov_b64_e32 v[42:43], v[10:11]
	v_mov_b64_e32 v[40:41], v[8:9]
	v_mov_b64_e32 v[38:39], v[6:7]
	v_mov_b64_e32 v[36:37], v[4:5]
	v_mov_b64_e32 v[34:35], v[2:3]
	v_mov_b64_e32 v[32:33], v[0:1]
	v_mov_b64_e32 v[60:61], v[12:13]
	v_mov_b64_e32 v[58:59], v[10:11]
	v_mov_b64_e32 v[56:57], v[8:9]
	v_mov_b64_e32 v[54:55], v[6:7]
	v_mov_b64_e32 v[52:53], v[4:5]
	v_mov_b64_e32 v[50:51], v[2:3]
	v_mov_b64_e32 v[48:49], v[0:1]
	v_mov_b64_e32 v[76:77], v[12:13]
	v_mov_b64_e32 v[74:75], v[10:11]
	v_mov_b64_e32 v[72:73], v[8:9]
	v_mov_b64_e32 v[70:71], v[6:7]
	v_mov_b64_e32 v[68:69], v[4:5]
	v_mov_b64_e32 v[66:67], v[2:3]
	v_mov_b64_e32 v[64:65], v[0:1]
	v_mov_b32_e32 v1, 0
	v_mov_b32_e32 v14, 0xf149f2ca
	s_waitcnt vmcnt(0)
	ds_write_b128 v195, v[132:135] offset:13312
	s_waitcnt lgkmcnt(0)
	s_barrier
	v_add3_u32 v15, 0, v251, v156
	v_add3_u32 v183, 0, v239, v155
	v_add_u32_e32 v187, 0x4600, v183
	v_add_u32_e32 v183, 0x3400, v183

; template <int DQ, bool NA, int NQG>
; DI void attn_wg(const half_t* Qp, const half_t* Kp, const half_t* Vp, int q0, bool active, int seg0_start, int seg0_tiles,
;                 int seg1_start, int seg1_tiles, const float* rpb_h, int rq, char* smem, int tid, f16v (&O)[2][NQG]) {
;     ...
;     if (need) {
; #pragma unroll 1
;       for (int st = 0; st < 2; ++st) {
;         f16v S[NQG];
; #pragma unroll
;         for (int qg = 0; qg < NQG; ++qg)
; #pragma unroll
;           for (int i = 0; i < 16; ++i) S[qg][i] = 0.f;
.LBB0_2039:
	v_cndmask_b32_e64 v2, 0, 1, s[14:15]
	v_cmp_ne_u32_e64 s[6:7], 1, v2
	s_andn2_b64 vcc, exec, s[14:15]
	s_cbranch_vccnz .LBB0_2046
	s_cmp_eq_u32 s18, 0
	s_cselect_b32 s19, 1, 0
	s_bitcmp1_b32 s18, 0
	s_cselect_b32 s18, 0x5800, 0
	s_cmp_lg_u32 s19, 0
	s_cbranch_scc0 .Lnoinit_diff1c
	v_mov_b32_e32 v196, 0
	v_mov_b32_e32 v197, 0
	v_mov_b32_e32 v198, 0
	v_mov_b32_e32 v199, 0
	v_mov_b32_e32 v200, 0
	v_mov_b32_e32 v201, 0
	v_mov_b32_e32 v202, 0
	v_mov_b32_e32 v203, 0
	v_mov_b32_e32 v204, 0
	v_mov_b32_e32 v205, 0
	v_mov_b32_e32 v206, 0
	v_mov_b32_e32 v207, 0
	v_mov_b32_e32 v208, 0
	v_mov_b32_e32 v209, 0
	v_mov_b32_e32 v210, 0
	v_mov_b32_e32 v211, 0
	v_mov_b32_e32 v212, 0
	v_mov_b32_e32 v213, 0
	v_mov_b32_e32 v214, 0
	v_mov_b32_e32 v215, 0
	v_mov_b32_e32 v216, 0
	v_mov_b32_e32 v217, 0
	v_mov_b32_e32 v218, 0
	v_mov_b32_e32 v219, 0
	v_mov_b32_e32 v220, 0
	v_mov_b32_e32 v221, 0
	v_mov_b32_e32 v222, 0
	v_mov_b32_e32 v223, 0
	v_mov_b32_e32 v224, 0
	v_mov_b32_e32 v225, 0
	v_mov_b32_e32 v226, 0
	v_mov_b32_e32 v227, 0

; template <int DQ, bool NA, int NQG>
; DI void attn_wg(const half_t* Qp, const half_t* Kp, const half_t* Vp, int q0, bool active, int seg0_start, int seg0_tiles,
;                 int seg1_start, int seg1_tiles, const float* rpb_h, int rq, char* smem, int tid, f16v (&O)[2][NQG]) {
;     ...
;           lrun[qg] += rs2.x + rs2.y;
; #pragma unroll
;           for (int dvt = 0; dvt < 2; ++dvt) {
; #pragma unroll
;             for (int sx = 0; sx < 2; ++sx) {
;               const h8 va = __builtin_shufflevector(vf[dvt][sx][0], vf[dvt][sx][1], 0, 1, 2, 3, 4, 5, 6, 7);
;               O[dvt][qg] = __builtin_amdgcn_mfma_f32_32x32x16_f16(va, P[sx], O[dvt][qg], 0, 0, 0);
;             }
.Lcont_diff1c_3:
	v_add_f32_e32 v1, v1, v80
	v_mfma_f32_32x32x16_f16 v[48:63], v[10:13], v[228:231], v[48:63]
	v_mfma_f32_32x32x16_f16 v[16:31], v[150:153], v[228:231], v[16:31]
	v_mfma_f32_32x32x16_f16 v[48:63], v[136:139], v[232:235], v[48:63]
	v_mfma_f32_32x32x16_f16 v[16:31], v[190:193], v[232:235], v[16:31]
	s_lshl_b32 s40, s18, 1
	s_sub_u32 s40, 0x5800, s40
	v_add_u32_e32 v15, s40, v15
	v_add_u32_e32 v183, s40, v183
	v_add_u32_e32 v187, s40, v187
	s_branch .Lend_diff1c

; template <int DQ, bool NA, int NQG>
; DI void attn_wg(const half_t* Qp, const half_t* Kp, const half_t* Vp, int q0, bool active, int seg0_start, int seg0_tiles,
;                 int seg1_start, int seg1_tiles, const float* rpb_h, int rq, char* smem, int tid, f16v (&O)[2][NQG]) {
;     ...
;   float mrun[NQG], lrun[NQG];
; #pragma unroll
;   for (int qg = 0; qg < NQG; ++qg) { mrun[qg] = -1e30f; lrun[qg] = 0.f; }
; #pragma unroll
;   for (int a = 0; a < 2; ++a)
; #pragma unroll
;     for (int c = 0; c < NQG; ++c)
; #pragma unroll
;       for (int i = 0; i < 16; ++i) O[a][c][i] = 0.f;
;   const int ntiles = seg0_tiles + seg1_tiles;
;   const int kc0 = tid, kc1 = tid + 512;
;   const half_t* kg0 = Kp + kc0 * 8;
;   const half_t* kg1 = Kp + kc1 * 8;
;   const half_t* vg = Vp + (size_t)(tid >> 3) * TOK + (tid & 7) * 8;
;   const int ks0 = (kc0 / CPK) * KSTR + (kc0 % CPK) * 8, ks1 = (kc1 / CPK) * KSTR + (kc1 % CPK) * 8, vs0 = (tid >> 3) * VSTR + (tid & 7) * 8;
;   uint4 kreg0 = {0, 0, 0, 0}, kreg1 = {0, 0, 0, 0}, vreg;
;   const int r0w = min(max(rq - 4, 0), 24);
;   {
;     const int k0 = (0 < seg0_tiles) ? seg0_start : seg1_start;
;     if (kc0 < KCH) kreg0 = *(const uint4*)(kg0 + (size_t)k0 * DQ);
;     if (DQ == 96 && kc1 < KCH) kreg1 = *(const uint4*)(kg1 + (size_t)k0 * DQ);
;     vreg = *(const uint4*)(vg + k0);
;     if (kc0 < KCH) *(uint4*)((half_t*)smem + ks0) = kreg0;
;     if (DQ == 96 && kc1 < KCH) *(uint4*)((half_t*)smem + ks1) = kreg1;
;     *(uint4*)((half_t*)(smem + ATT_VOFF) + vs0) = vreg;
;   }
;   __syncthreads();
;     ...
;     const half_t* ksm = (const half_t*)(smem + (it & 1) * ATT_STAGE) + r * KSTR + h * 8;
;     const half_t* vsm = (const half_t*)(smem + (it & 1) * ATT_STAGE + ATT_VOFF) + r * VSTR + h * 4;
.LBB0_2056:
	s_or_b64 exec, exec, s[14:15]
	v_mov_b32_e32 v14, v0
	v_mov_b32_e32 v15, v0
	v_mov_b32_e32 v1, v0
	v_mov_b32_e32 v2, v0
	v_mov_b32_e32 v3, v0
	v_mov_b32_e32 v4, v0
	v_mov_b32_e32 v5, v0
	v_mov_b32_e32 v6, v0
	v_mov_b32_e32 v7, v0
	v_mov_b32_e32 v8, v0
	v_mov_b32_e32 v9, v0
	v_mov_b32_e32 v10, v0
	v_mov_b32_e32 v11, v0
	v_mov_b32_e32 v12, v0
	v_mov_b32_e32 v13, v0
	v_mov_b64_e32 v[30:31], v[14:15]
	v_mov_b64_e32 v[62:63], v[14:15]
	v_mov_b64_e32 v[46:47], v[14:15]
	v_mov_b64_e32 v[78:79], v[14:15]
	s_mov_b32 s19, 0
	v_mov_b32_e32 v144, 0xf149f2ca
	v_mov_b32_e32 v145, 0
	v_mov_b64_e32 v[28:29], v[12:13]
	v_mov_b64_e32 v[26:27], v[10:11]
	v_mov_b64_e32 v[24:25], v[8:9]
	v_mov_b64_e32 v[22:23], v[6:7]
	v_mov_b64_e32 v[20:21], v[4:5]
	v_mov_b64_e32 v[18:19], v[2:3]
	v_mov_b64_e32 v[16:17], v[0:1]
	v_mov_b64_e32 v[60:61], v[12:13]
	v_mov_b64_e32 v[58:59], v[10:11]
	v_mov_b64_e32 v[56:57], v[8:9]
	v_mov_b64_e32 v[54:55], v[6:7]
	v_mov_b64_e32 v[52:53], v[4:5]
	v_mov_b64_e32 v[50:51], v[2:3]
	v_mov_b64_e32 v[48:49], v[0:1]
	v_mov_b64_e32 v[44:45], v[12:13]
	v_mov_b64_e32 v[42:43], v[10:11]
	v_mov_b64_e32 v[40:41], v[8:9]
	v_mov_b64_e32 v[38:39], v[6:7]
	v_mov_b64_e32 v[36:37], v[4:5]
	v_mov_b64_e32 v[34:35], v[2:3]
	v_mov_b64_e32 v[32:33], v[0:1]
	v_mov_b64_e32 v[76:77], v[12:13]
	v_mov_b64_e32 v[74:75], v[10:11]
	v_mov_b64_e32 v[72:73], v[8:9]
	v_mov_b64_e32 v[70:71], v[6:7]
	v_mov_b64_e32 v[68:69], v[4:5]
	v_mov_b64_e32 v[66:67], v[2:3]
	v_mov_b64_e32 v[64:65], v[0:1]
	v_mov_b32_e32 v1, 0
	v_mov_b32_e32 v14, 0xf149f2ca
	s_waitcnt vmcnt(0)
	ds_write_b128 v195, v[132:135] offset:13312
	s_waitcnt lgkmcnt(0)
	s_barrier
	v_add3_u32 v15, 0, v251, v156
	v_add3_u32 v151, 0, v239, v155
	v_add_u32_e32 v152, 0x4600, v151
	v_add_u32_e32 v151, 0x3400, v151

; template <int DQ, bool NA, int NQG>
; DI void attn_wg(const half_t* Qp, const half_t* Kp, const half_t* Vp, int q0, bool active, int seg0_start, int seg0_tiles,
;                 int seg1_start, int seg1_tiles, const float* rpb_h, int rq, char* smem, int tid, f16v (&O)[2][NQG]) {
;     ...
;     if (need) {
; #pragma unroll 1
;       for (int st = 0; st < 2; ++st) {
;         f16v S[NQG];
; #pragma unroll
;         for (int qg = 0; qg < NQG; ++qg)
; #pragma unroll
;           for (int i = 0; i < 16; ++i) S[qg][i] = 0.f;
.LBB0_2061:
	s_and_b64 vcc, exec, s[6:7]
	s_cbranch_vccnz .LBB0_2068
	s_cmp_eq_u32 s19, 0
	s_cselect_b32 s17, 1, 0
	s_bitcmp1_b32 s19, 0
	s_cselect_b32 s16, 0x5800, 0
	s_cmp_lg_u32 s17, 0
	s_cbranch_scc0 .Lnoinit_diff2c
	v_mov_b32_e32 v196, 0
	v_mov_b32_e32 v197, 0
	v_mov_b32_e32 v198, 0
	v_mov_b32_e32 v199, 0
	v_mov_b32_e32 v200, 0
	v_mov_b32_e32 v201, 0
	v_mov_b32_e32 v202, 0
	v_mov_b32_e32 v203, 0
	v_mov_b32_e32 v204, 0
	v_mov_b32_e32 v205, 0
	v_mov_b32_e32 v206, 0
	v_mov_b32_e32 v207, 0
	v_mov_b32_e32 v208, 0
	v_mov_b32_e32 v209, 0
	v_mov_b32_e32 v210, 0
	v_mov_b32_e32 v211, 0
	v_mov_b32_e32 v212, 0
	v_mov_b32_e32 v213, 0
	v_mov_b32_e32 v214, 0
	v_mov_b32_e32 v215, 0
	v_mov_b32_e32 v216, 0
	v_mov_b32_e32 v217, 0
	v_mov_b32_e32 v218, 0
	v_mov_b32_e32 v219, 0
	v_mov_b32_e32 v220, 0
	v_mov_b32_e32 v221, 0
	v_mov_b32_e32 v222, 0
	v_mov_b32_e32 v223, 0
	v_mov_b32_e32 v224, 0
	v_mov_b32_e32 v225, 0
	v_mov_b32_e32 v226, 0
	v_mov_b32_e32 v227, 0

; template <int DQ, bool NA, int NQG>
; DI void attn_wg(const half_t* Qp, const half_t* Kp, const half_t* Vp, int q0, bool active, int seg0_start, int seg0_tiles,
;                 int seg1_start, int seg1_tiles, const float* rpb_h, int rq, char* smem, int tid, f16v (&O)[2][NQG]) {
;     ...
;           lrun[qg] += rs2.x + rs2.y;
; #pragma unroll
;           for (int dvt = 0; dvt < 2; ++dvt) {
; #pragma unroll
;             for (int sx = 0; sx < 2; ++sx) {
;               const h8 va = __builtin_shufflevector(vf[dvt][sx][0], vf[dvt][sx][1], 0, 1, 2, 3, 4, 5, 6, 7);
;               O[dvt][qg] = __builtin_amdgcn_mfma_f32_32x32x16_f16(va, P[sx], O[dvt][qg], 0, 0, 0);
;             }
.Lcont_diff2c_3:
	v_add_f32_e32 v1, v1, v80
	v_mfma_f32_32x32x16_f16 v[32:47], v[10:13], v[228:231], v[32:47]
	v_mfma_f32_32x32x16_f16 v[16:31], v[146:149], v[228:231], v[16:31]
	v_mfma_f32_32x32x16_f16 v[32:47], v[136:139], v[232:235], v[32:47]
	v_mfma_f32_32x32x16_f16 v[16:31], v[190:193], v[232:235], v[16:31]
	s_lshl_b32 s40, s16, 1
	s_sub_u32 s40, 0x5800, s40
	v_add_u32_e32 v15, s40, v15
	v_add_u32_e32 v151, s40, v151
	v_add_u32_e32 v152, s40, v152
	s_branch .Lend_diff2c
